# v64 plus the sample-scan unit folded into the helper waves (intervals 0-17), converter items from interval 18 (shared registers)
# speedup vs baseline: 1.0084x; 1.0084x over previous
.Lhs_p1l_skip:
	v_mov_b32_e32 v48, 0x3fb8aa3b
	v_mov_b32_e32 v49, 0x3fb8aa3b
	s_mul_i32 s0, s48, 0x810
	v_add_u32_e32 v209, s0, v206
	v_mov_b32_e32 v211, 0
	v_lshlrev_b32_e32 v210, 1, v208
	s_movk_i32 s14, 0x1a00
	v_mad_u64_u32 v[182:183], s[0:1], v209, s14, v[210:211]
	s_add_u32 s4, s86, 0x81a7000
	s_addc_u32 s5, s87, 0
	v_lshl_add_u64 v[182:183], v[182:183], 0, s[4:5]
	s_mov_b64 s[0:1], 0x1000
	v_lshl_add_u64 v[178:179], v[182:183], 0, s[0:1]
	v_lshl_add_u64 v[180:181], v[178:179], 0, s[0:1]
	v_lshl_add_u32 v198, v209, 11, v210
	v_mov_b32_e32 v210, v198
	s_add_u32 s4, s86, 0xeb48000
	s_addc_u32 s5, s87, 0
	v_lshl_add_u64 v[186:187], v[210:211], 0, s[4:5]
	s_add_u32 s4, s86, 0x10bc8000
	s_addc_u32 s5, s87, 0
	v_lshl_add_u64 v[188:189], v[210:211], 0, s[4:5]
	s_lshl_b32 s0, s9, 6
	s_lshl_b32 s1, s10, 5
	s_add_i32 s0, s0, s1
	v_lshl_add_u32 v198, v207, 2, s0
	v_lshlrev_b32_e32 v198, 1, v198
	v_lshl_add_u32 v210, v209, 11, v198
	s_add_u32 s4, s86, 0x5700000
	s_addc_u32 s5, s87, 0
	v_lshl_add_u64 v[190:191], v[210:211], 0, s[4:5]
	s_lshl_b32 s0, s9, 2
	v_lshl_add_u32 v210, v209, 6, s0
	s_add_u32 s4, s86, 0x7884000
	s_addc_u32 s5, s87, 0
	v_lshl_add_u64 v[192:193], v[210:211], 0, s[4:5]
	v_mul_u32_u24_e32 v194, 0x600, v206
	v_lshl_add_u32 v194, v207, 4, v194
	s_lshl_b32 s0, s10, 7
	v_mul_u32_u24_e32 v222, 0x600, v206
	v_lshl_add_u32 v222, v207, 4, v222
	v_add_u32_e32 v222, s0, v222
	v_lshlrev_b32_e32 v195, 7, v206
	v_lshl_add_u32 v195, v207, 4, v195
	v_add_u32_e32 v195, 0x18000, v195
	v_lshlrev_b32_e32 v196, 2, v206
	v_add_u32_e32 v196, 0x1a000, v196
	v_lshlrev_b32_e32 v197, 3, v206
	v_add_u32_e32 v197, 0x1a100, v197
	s_lshl_b32 s50, s55, 4
	s_add_i32 s50, s50, s46
	s_lshl_b32 s51, s10, 3
	s_add_i32 s50, s50, s51
	s_lshl_b32 s50, s50, 14
	v_lshlrev_b32_e32 v210, 8, v206
	v_lshl_add_u32 v210, v207, 4, v210
	v_add_u32_e32 v210, s50, v210
	v_readlane_b32 s52, v254, 39
	v_readlane_b32 s53, v254, 40
	v_readlane_b32 s56, v255, 26
	v_readlane_b32 s57, v255, 27
	s_nop 4
	v_lshl_add_u64 v[250:251], v[210:211], 0, s[52:53]
	v_lshl_add_u64 v[236:237], v[210:211], 0, s[56:57]
	v_lshlrev_b32_e32 v238, 4, v207
	v_add_u32_e32 v238, 0x1d000, v238
	v_lshlrev_b32_e32 v239, 2, v206
	v_add_u32_e32 v240, 0x1a400, v239
	v_add_u32_e32 v239, 0x1d500, v239
	v_and_b32_e32 v231, 63, v241
	v_and_b32_e32 v51, 1, v231
	v_and_b32_e32 v233, 62, v231
	v_lshlrev_b32_e32 v233, 1, v233
	v_lshlrev_b32_e32 v50, 2, v231
	s_mov_b32 s34, 0
	global_load_dwordx2 v[52:53], v[178:179], off
	global_load_dwordx2 v[54:55], v[178:179], off offset:64
	global_load_dwordx2 v[56:57], v[178:179], off offset:2048
	global_load_dwordx2 v[58:59], v[178:179], off offset:2112
	global_load_dwordx2 v[60:61], v[180:181], off
	global_load_dwordx2 v[62:63], v[180:181], off offset:64
	global_load_dwordx2 v[64:65], v[182:183], off offset:-2560
	global_load_dwordx2 v[66:67], v[182:183], off offset:-2496
	global_load_dwordx2 v[68:69], v[182:183], off offset:-512
	global_load_dwordx2 v[70:71], v[182:183], off offset:-448
	global_load_dwordx2 v[72:73], v[178:179], off offset:-2560
	global_load_dwordx2 v[74:75], v[178:179], off offset:-2496
	global_load_dwordx2 v[76:77], v[186:187], off
	global_load_dwordx2 v[78:79], v[186:187], off offset:64
	global_load_dwordx2 v[80:81], v[188:189], off
	global_load_dwordx2 v[82:83], v[188:189], off offset:64
	s_mov_b32 s13, 0
	s_waitcnt vmcnt(0)
	s_cmp_lt_u32 s11, 6
	s_cbranch_scc0 .Lhs_p1c_skip
	v_lshlrev_b32_e32 v130, 16, v120
	v_and_b32_e32 v131, 0xffff0000, v120
	v_lshlrev_b32_e32 v132, 16, v121
	v_and_b32_e32 v133, 0xffff0000, v121
	v_lshlrev_b32_e32 v134, 16, v122
	v_and_b32_e32 v135, 0xffff0000, v122
	v_lshlrev_b32_e32 v136, 16, v123
	v_and_b32_e32 v137, 0xffff0000, v123
	v_lshlrev_b32_e32 v138, 16, v124
	v_and_b32_e32 v139, 0xffff0000, v124
	v_lshlrev_b32_e32 v140, 16, v125
	v_and_b32_e32 v141, 0xffff0000, v125
	v_lshlrev_b32_e32 v142, 16, v126
	v_and_b32_e32 v143, 0xffff0000, v126
	v_lshlrev_b32_e32 v144, 16, v127
	v_and_b32_e32 v145, 0xffff0000, v127
	v_lshlrev_b32_e32 v146, 16, v128
	v_and_b32_e32 v147, 0xffff0000, v128
	v_lshlrev_b32_e32 v148, 16, v129
	v_and_b32_e32 v149, 0xffff0000, v129
	v_pk_add_f32 v[158:159], v[84:85], v[130:131] neg_lo:[0,1] neg_hi:[0,1]
	v_pk_add_f32 v[160:161], v[86:87], v[132:133] neg_lo:[0,1] neg_hi:[0,1]
	v_pk_fma_f32 v[130:131], v[158:159], v[96:97], v[130:131]
	v_pk_fma_f32 v[132:133], v[160:161], v[98:99], v[132:133]
	v_pk_add_f32 v[158:159], v[88:89], v[134:135] neg_lo:[0,1] neg_hi:[0,1]
	v_pk_add_f32 v[160:161], v[90:91], v[136:137] neg_lo:[0,1] neg_hi:[0,1]
	v_pk_fma_f32 v[134:135], v[158:159], v[100:101], v[134:135]
	v_pk_fma_f32 v[136:137], v[160:161], v[102:103], v[136:137]
	v_pk_add_f32 v[158:159], v[92:93], v[138:139] neg_lo:[0,1] neg_hi:[0,1]
	v_pk_add_f32 v[160:161], v[94:95], v[140:141] neg_lo:[0,1] neg_hi:[0,1]
	v_pk_fma_f32 v[138:139], v[158:159], v[104:105], v[138:139]
	v_pk_fma_f32 v[140:141], v[160:161], v[106:107], v[140:141]
	v_pk_mul_f32 v[150:151], v[134:135], v[108:109]
	v_pk_mul_f32 v[152:153], v[136:137], v[110:111]
	v_pk_add_f32 v[158:159], v[146:147], -1.0 op_sel_hi:[1,0]
	v_pk_add_f32 v[160:161], v[148:149], -1.0 op_sel_hi:[1,0]
	v_pk_fma_f32 v[158:159], v[112:113], v[158:159], 1.0 op_sel_hi:[1,1,0]
	v_pk_fma_f32 v[160:161], v[114:115], v[160:161], 1.0 op_sel_hi:[1,1,0]
	v_pk_mul_f32 v[154:155], v[134:135], v[158:159]
	v_pk_mul_f32 v[156:157], v[136:137], v[160:161]
	v_pk_mul_f32 v[158:159], v[130:131], v[154:155]
	v_pk_mul_f32 v[160:161], v[132:133], v[156:157]
	v_pk_mul_f32 v[162:163], v[158:159], v[116:117]
	v_pk_mul_f32 v[164:165], v[160:161], v[118:119]
	v_pk_add_f32 v[162:163], v[162:163], v[164:165]
	v_pk_mul_f32 v[158:159], v[150:151], v[150:151]
	v_pk_mul_f32 v[160:161], v[152:153], v[152:153]
	v_add_f32_e32 v167, v162, v163
	v_pk_add_f32 v[158:159], v[158:159], v[160:161]
	v_mul_f32_e32 v142, 0x3fb8aa3b, v142
	v_mul_f32_e32 v143, 0x3fb8aa3b, v143
	v_mul_f32_e32 v144, 0x3fb8aa3b, v144
	v_mul_f32_e32 v145, 0x3fb8aa3b, v145
	v_add_f32_e32 v166, v158, v159
	v_exp_f32_e32 v142, v142
	v_exp_f32_e32 v143, v143
	v_exp_f32_e32 v144, v144
	v_exp_f32_e32 v145, v145
	v_add_f32_dpp v166, v166, v166 quad_perm:[1,0,3,2] row_mask:0xf bank_mask:0xf bound_ctrl:1
	v_add_f32_dpp v167, v167, v167 quad_perm:[1,0,3,2] row_mask:0xf bank_mask:0xf bound_ctrl:1
	s_nop 0
	v_add_f32_dpp v166, v166, v166 quad_perm:[2,3,0,1] row_mask:0xf bank_mask:0xf bound_ctrl:1
	v_add_f32_dpp v167, v167, v167 quad_perm:[2,3,0,1] row_mask:0xf bank_mask:0xf bound_ctrl:1
	s_nop 0
	v_add_f32_dpp v166, v166, v166 row_half_mirror row_mask:0xf bank_mask:0xf bound_ctrl:1
	v_add_f32_dpp v167, v167, v167 row_half_mirror row_mask:0xf bank_mask:0xf bound_ctrl:1
	s_nop 0
	v_add_f32_dpp v166, v166, v166 row_ror:8 row_mask:0xf bank_mask:0xf bound_ctrl:1
	v_add_f32_dpp v167, v167, v167 row_ror:8 row_mask:0xf bank_mask:0xf bound_ctrl:1
	v_rsq_f32_e32 v168, v166
	v_mul_u32_u24_e32 v173, 0x600, v172
	v_lshl_add_u32 v173, v174, 4, v173
	v_add_u32_e32 v173, 0x1d000, v173
	v_min_f32_e32 v168, 0x5368d4a5, v168
	v_pk_mul_f32 v[158:159], v[150:151], v[168:169] op_sel_hi:[1,0] neg_lo:[1,0] neg_hi:[1,0]
	v_pk_mul_f32 v[160:161], v[152:153], v[168:169] op_sel_hi:[1,0] neg_lo:[1,0] neg_hi:[1,0]
	v_pk_mul_f32 v[162:163], v[150:151], v[168:169] op_sel_hi:[1,0]
	v_pk_mul_f32 v[164:165], v[152:153], v[168:169] op_sel_hi:[1,0]
	v_pk_mul_f32 v[162:163], v[162:163], v[146:147]
	v_pk_mul_f32 v[164:165], v[164:165], v[148:149]
	v_lshlrev_b32_e32 v172, 2, v172
	v_add_u32_e32 v172, 0x1ac00, v172
	ds_write_b128 v173, v[130:133]
	ds_write_b128 v173, v[142:145] offset:256
	ds_write_b128 v173, v[154:157] offset:512
	ds_write_b128 v173, v[158:161] offset:768
	ds_write_b128 v173, v[162:165] offset:1024
	ds_write_b128 v173, v[138:141] offset:1280
	ds_write_b32 v172, v167

.Lh_nopost:
	s_cmp_lt_u32 s12, 64
	s_cbranch_scc0 .Lh_nobuild
	s_add_i32 s13, s12, 1
	s_and_b32 s13, s13, 1
	s_waitcnt vmcnt(1)
	v_lshlrev_b32_e32 v84, 16, v52
	v_and_b32_e32 v85, 0xffff0000, v52
	v_lshlrev_b32_e32 v86, 16, v53
	v_and_b32_e32 v87, 0xffff0000, v53
	v_lshlrev_b32_e32 v88, 16, v54
	v_and_b32_e32 v89, 0xffff0000, v54
	v_lshlrev_b32_e32 v90, 16, v55
	v_and_b32_e32 v91, 0xffff0000, v55
	v_lshlrev_b32_e32 v124, 16, v64
	v_and_b32_e32 v125, 0xffff0000, v64
	v_lshlrev_b32_e32 v126, 16, v65
	v_and_b32_e32 v127, 0xffff0000, v65
	v_lshlrev_b32_e32 v128, 16, v66
	v_and_b32_e32 v129, 0xffff0000, v66
	v_lshlrev_b32_e32 v130, 16, v67
	v_and_b32_e32 v131, 0xffff0000, v67
	v_pk_add_f32 v[124:125], v[124:125], v[84:85] neg_lo:[0,1] neg_hi:[0,1]
	v_pk_add_f32 v[126:127], v[126:127], v[86:87] neg_lo:[0,1] neg_hi:[0,1]
	v_pk_add_f32 v[128:129], v[128:129], v[88:89] neg_lo:[0,1] neg_hi:[0,1]
	v_pk_add_f32 v[130:131], v[130:131], v[90:91] neg_lo:[0,1] neg_hi:[0,1]
	v_pk_fma_f32 v[84:85], v[0:1], v[124:125], v[84:85]
	v_pk_fma_f32 v[86:87], v[2:3], v[126:127], v[86:87]
	v_pk_fma_f32 v[88:89], v[4:5], v[128:129], v[88:89]
	v_pk_fma_f32 v[90:91], v[6:7], v[130:131], v[90:91]
	v_lshlrev_b32_e32 v92, 16, v56
	v_and_b32_e32 v93, 0xffff0000, v56
	v_lshlrev_b32_e32 v94, 16, v57
	v_and_b32_e32 v95, 0xffff0000, v57
	v_lshlrev_b32_e32 v96, 16, v58
	v_and_b32_e32 v97, 0xffff0000, v58
	v_lshlrev_b32_e32 v98, 16, v59
	v_and_b32_e32 v99, 0xffff0000, v59
	v_lshlrev_b32_e32 v124, 16, v68
	v_and_b32_e32 v125, 0xffff0000, v68
	v_lshlrev_b32_e32 v126, 16, v69
	v_and_b32_e32 v127, 0xffff0000, v69
	v_lshlrev_b32_e32 v128, 16, v70
	v_and_b32_e32 v129, 0xffff0000, v70
	v_lshlrev_b32_e32 v130, 16, v71
	v_and_b32_e32 v131, 0xffff0000, v71
	v_pk_add_f32 v[124:125], v[124:125], v[92:93] neg_lo:[0,1] neg_hi:[0,1]
	v_pk_add_f32 v[126:127], v[126:127], v[94:95] neg_lo:[0,1] neg_hi:[0,1]
	v_pk_add_f32 v[128:129], v[128:129], v[96:97] neg_lo:[0,1] neg_hi:[0,1]
	v_pk_add_f32 v[130:131], v[130:131], v[98:99] neg_lo:[0,1] neg_hi:[0,1]
	v_pk_fma_f32 v[92:93], v[8:9], v[124:125], v[92:93]
	v_pk_fma_f32 v[94:95], v[10:11], v[126:127], v[94:95]
	v_pk_fma_f32 v[96:97], v[12:13], v[128:129], v[96:97]
	v_pk_fma_f32 v[98:99], v[14:15], v[130:131], v[98:99]
	v_lshlrev_b32_e32 v100, 16, v60
	v_and_b32_e32 v101, 0xffff0000, v60
	v_lshlrev_b32_e32 v102, 16, v61
	v_and_b32_e32 v103, 0xffff0000, v61
	v_lshlrev_b32_e32 v104, 16, v62
	v_and_b32_e32 v105, 0xffff0000, v62
	v_lshlrev_b32_e32 v106, 16, v63
	v_and_b32_e32 v107, 0xffff0000, v63
	v_lshlrev_b32_e32 v124, 16, v72
	v_and_b32_e32 v125, 0xffff0000, v72
	v_lshlrev_b32_e32 v126, 16, v73
	v_and_b32_e32 v127, 0xffff0000, v73
	v_lshlrev_b32_e32 v128, 16, v74
	v_and_b32_e32 v129, 0xffff0000, v74
	v_lshlrev_b32_e32 v130, 16, v75
	v_and_b32_e32 v131, 0xffff0000, v75
	v_pk_add_f32 v[124:125], v[124:125], v[100:101] neg_lo:[0,1] neg_hi:[0,1]
	v_pk_add_f32 v[126:127], v[126:127], v[102:103] neg_lo:[0,1] neg_hi:[0,1]
	v_pk_add_f32 v[128:129], v[128:129], v[104:105] neg_lo:[0,1] neg_hi:[0,1]
	v_pk_add_f32 v[130:131], v[130:131], v[106:107] neg_lo:[0,1] neg_hi:[0,1]
	v_pk_fma_f32 v[100:101], v[16:17], v[124:125], v[100:101]
	v_pk_fma_f32 v[102:103], v[18:19], v[126:127], v[102:103]
	v_pk_fma_f32 v[104:105], v[20:21], v[128:129], v[104:105]
	v_pk_fma_f32 v[106:107], v[22:23], v[130:131], v[106:107]
	v_lshlrev_b32_e32 v108, 16, v80
	v_and_b32_e32 v109, 0xffff0000, v80
	v_lshlrev_b32_e32 v110, 16, v81
	v_and_b32_e32 v111, 0xffff0000, v81
	v_lshlrev_b32_e32 v112, 16, v82
	v_and_b32_e32 v113, 0xffff0000, v82
	v_lshlrev_b32_e32 v114, 16, v83
	v_and_b32_e32 v115, 0xffff0000, v83
	v_lshlrev_b32_e32 v116, 16, v76
	v_and_b32_e32 v117, 0xffff0000, v76
	v_lshlrev_b32_e32 v118, 16, v77
	v_and_b32_e32 v119, 0xffff0000, v77
	v_lshlrev_b32_e32 v120, 16, v78
	v_and_b32_e32 v121, 0xffff0000, v78
	v_lshlrev_b32_e32 v122, 16, v79
	v_and_b32_e32 v123, 0xffff0000, v79
	v_pk_mul_f32 v[132:133], v[92:93], v[24:25]
	v_pk_mul_f32 v[134:135], v[94:95], v[26:27]
	v_pk_mul_f32 v[136:137], v[96:97], v[28:29]
	v_pk_mul_f32 v[138:139], v[98:99], v[30:31]
	v_pk_add_f32 v[124:125], v[108:109], -1.0 op_sel_hi:[1,0]
	v_pk_add_f32 v[126:127], v[110:111], -1.0 op_sel_hi:[1,0]
	v_pk_add_f32 v[128:129], v[112:113], -1.0 op_sel_hi:[1,0]
	v_pk_add_f32 v[130:131], v[114:115], -1.0 op_sel_hi:[1,0]
	v_pk_fma_f32 v[124:125], v[32:33], v[124:125], 1.0 op_sel_hi:[1,1,0]
	v_pk_fma_f32 v[126:127], v[34:35], v[126:127], 1.0 op_sel_hi:[1,1,0]
	v_pk_fma_f32 v[128:129], v[36:37], v[128:129], 1.0 op_sel_hi:[1,1,0]
	v_pk_fma_f32 v[130:131], v[38:39], v[130:131], 1.0 op_sel_hi:[1,1,0]
	v_pk_mul_f32 v[140:141], v[124:125], v[92:93]
	v_pk_mul_f32 v[142:143], v[126:127], v[94:95]
	v_pk_mul_f32 v[144:145], v[128:129], v[96:97]
	v_pk_mul_f32 v[146:147], v[130:131], v[98:99]
	v_pk_mul_f32 v[148:149], v[84:85], v[140:141]
	v_pk_mul_f32 v[150:151], v[86:87], v[142:143]
	v_pk_mul_f32 v[152:153], v[88:89], v[144:145]
	v_pk_mul_f32 v[154:155], v[90:91], v[146:147]
	v_pk_mul_f32 v[156:157], v[132:133], v[108:109]
	v_pk_mul_f32 v[158:159], v[134:135], v[110:111]
	v_pk_mul_f32 v[160:161], v[136:137], v[112:113]
	v_pk_mul_f32 v[162:163], v[138:139], v[114:115]
	v_pk_mul_f32 v[124:125], v[148:149], v[40:41]
	v_pk_mul_f32 v[126:127], v[150:151], v[42:43]
	v_pk_mul_f32 v[128:129], v[152:153], v[44:45]
	v_pk_mul_f32 v[130:131], v[154:155], v[46:47]
	v_pk_add_f32 v[124:125], v[124:125], v[126:127]
	v_pk_add_f32 v[128:129], v[128:129], v[130:131]
	v_pk_add_f32 v[124:125], v[124:125], v[128:129]
	v_add_f32_e32 v173, v124, v125
	v_pk_mul_f32 v[124:125], v[156:157], v[84:85]
	v_pk_mul_f32 v[126:127], v[158:159], v[86:87]
	v_pk_mul_f32 v[128:129], v[160:161], v[88:89]
	v_pk_mul_f32 v[130:131], v[162:163], v[90:91]
	v_pk_add_f32 v[124:125], v[124:125], v[126:127]
	v_pk_add_f32 v[128:129], v[128:129], v[130:131]
	v_pk_add_f32 v[124:125], v[124:125], v[128:129]
	v_add_f32_e32 v174, v124, v125
	v_pk_mul_f32 v[124:125], v[132:133], v[132:133]
	v_pk_mul_f32 v[126:127], v[134:135], v[134:135]
	v_pk_mul_f32 v[128:129], v[136:137], v[136:137]
	v_pk_mul_f32 v[130:131], v[138:139], v[138:139]
	v_pk_add_f32 v[124:125], v[124:125], v[126:127]
	v_pk_add_f32 v[128:129], v[128:129], v[130:131]
	v_pk_add_f32 v[124:125], v[124:125], v[128:129]
	v_add_f32_e32 v172, v124, v125
	v_pk_add_f32 v[148:149], v[148:149], v[150:151]
	v_pk_add_f32 v[152:153], v[152:153], v[154:155]
	v_pk_add_f32 v[148:149], v[148:149], v[152:153]
	v_add_f32_e32 v175, v148, v149
	v_pk_mul_f32 v[116:117], v[116:117], v[48:49]
	v_pk_mul_f32 v[118:119], v[118:119], v[48:49]
	v_pk_mul_f32 v[120:121], v[120:121], v[48:49]
	v_pk_mul_f32 v[122:123], v[122:123], v[48:49]
	v_add_f32_dpp v172, v172, v172 quad_perm:[1,0,3,2] row_mask:0xf bank_mask:0xf bound_ctrl:1
	v_add_f32_dpp v173, v173, v173 quad_perm:[1,0,3,2] row_mask:0xf bank_mask:0xf bound_ctrl:1
	v_add_f32_dpp v174, v174, v174 quad_perm:[1,0,3,2] row_mask:0xf bank_mask:0xf bound_ctrl:1
	v_add_f32_dpp v175, v175, v175 quad_perm:[1,0,3,2] row_mask:0xf bank_mask:0xf bound_ctrl:1
	v_add_f32_dpp v172, v172, v172 quad_perm:[2,3,0,1] row_mask:0xf bank_mask:0xf bound_ctrl:1
	v_add_f32_dpp v173, v173, v173 quad_perm:[2,3,0,1] row_mask:0xf bank_mask:0xf bound_ctrl:1
	v_add_f32_dpp v174, v174, v174 quad_perm:[2,3,0,1] row_mask:0xf bank_mask:0xf bound_ctrl:1
	v_add_f32_dpp v175, v175, v175 quad_perm:[2,3,0,1] row_mask:0xf bank_mask:0xf bound_ctrl:1
	v_add_f32_dpp v172, v172, v172 row_half_mirror row_mask:0xf bank_mask:0xf bound_ctrl:1
	v_add_f32_dpp v173, v173, v173 row_half_mirror row_mask:0xf bank_mask:0xf bound_ctrl:1
	v_add_f32_dpp v174, v174, v174 row_half_mirror row_mask:0xf bank_mask:0xf bound_ctrl:1
	v_add_f32_dpp v175, v175, v175 row_half_mirror row_mask:0xf bank_mask:0xf bound_ctrl:1
	v_exp_f32_e32 v116, v116
	v_exp_f32_e32 v117, v117
	v_exp_f32_e32 v118, v118
	v_exp_f32_e32 v119, v119
	v_exp_f32_e32 v120, v120
	v_exp_f32_e32 v121, v121
	v_exp_f32_e32 v122, v122
	v_exp_f32_e32 v123, v123
	v_rsq_f32_e32 v176, v172
	v_pk_mul_f32 v[148:149], v[116:117], v[84:85]
	v_pk_mul_f32 v[150:151], v[118:119], v[86:87]
	v_pk_mul_f32 v[152:153], v[120:121], v[88:89]
	v_pk_mul_f32 v[154:155], v[122:123], v[90:91]
	v_min_f32_e32 v176, 0x5368d4a5, v176
	v_mul_f32_e32 v174, v174, v176
	v_pk_mul_f32 v[164:165], v[132:133], v[176:177] op_sel_hi:[1,0] neg_lo:[1,0] neg_hi:[1,0]
	v_pk_mul_f32 v[166:167], v[134:135], v[176:177] op_sel_hi:[1,0] neg_lo:[1,0] neg_hi:[1,0]
	v_pk_mul_f32 v[168:169], v[136:137], v[176:177] op_sel_hi:[1,0] neg_lo:[1,0] neg_hi:[1,0]
	v_pk_mul_f32 v[170:171], v[138:139], v[176:177] op_sel_hi:[1,0] neg_lo:[1,0] neg_hi:[1,0]
	v_pk_mul_f32 v[156:157], v[156:157], v[176:177] op_sel_hi:[1,0]
	v_pk_mul_f32 v[158:159], v[158:159], v[176:177] op_sel_hi:[1,0]
	v_pk_mul_f32 v[160:161], v[160:161], v[176:177] op_sel_hi:[1,0]
	v_pk_mul_f32 v[162:163], v[162:163], v[176:177] op_sel_hi:[1,0]
	s_mul_i32 s14, s13, 0xc000
	v_add_u32_e32 v198, s14, v194
	ds_write_b128 v198, v[148:151] offset:0
	ds_write_b128 v198, v[152:155] offset:128
	ds_write_b128 v198, v[116:119] offset:256
	ds_write_b128 v198, v[120:123] offset:384
	ds_write_b128 v198, v[140:143] offset:512
	ds_write_b128 v198, v[144:147] offset:640
	ds_write_b128 v198, v[164:167] offset:768
	ds_write_b128 v198, v[168:171] offset:896
	ds_write_b128 v198, v[156:159] offset:1024
	ds_write_b128 v198, v[160:163] offset:1152
	ds_write_b128 v198, v[100:103] offset:1280
	ds_write_b128 v198, v[104:107] offset:1408
	s_lshl_b32 s14, s13, 7
	v_add_u32_e32 v199, s14, v196
	s_lshl_b32 s14, s13, 8
	v_add_u32_e32 v198, s14, v197
	ds_write_b32 v199, v173
	ds_write_b64 v198, v[174:175]
	s_sub_u32 s0, s12, 1
	s_cmp_lt_u32 s0, 16
	s_cbranch_scc0 .Lhs_noproc
	s_mov_b32 s50, s0
	s_lshr_b32 s51, s50, 1
	s_and_b32 s52, s50, 1
	s_mul_i32 s53, s51, 0x600
	v_add_u32_e32 v198, s53, v238
	s_lshl_b32 s54, s52, 7
	s_add_i32 s53, s53, s54
	v_add_u32_e32 v199, s53, v239
	ds_read_b128 v[84:87], v198 offset:768
	ds_read_b128 v[88:91], v198 offset:896
	ds_read_b128 v[92:95], v198 offset:256
	ds_read_b128 v[96:99], v198 offset:384
	ds_read_b128 v[100:103], v198 offset:1024
	ds_read_b128 v[104:107], v198 offset:1152
	ds_read_b128 v[108:111], v198 offset:512
	ds_read_b128 v[112:115], v198 offset:640
	ds_read_b128 v[116:119], v198
	ds_read_b128 v[120:123], v198 offset:128
	ds_read_b32 v124, v199
	s_lshl_b32 s53, s51, 8
	s_add_i32 s53, s53, s54
	v_add_u32_e32 v205, s53, v240
	s_waitcnt lgkmcnt(0)
	v_pk_mul_f32 v[128:129], v[242:243], v[84:85]
	v_pk_fma_f32 v[128:129], v[244:245], v[86:87], v[128:129]
	v_pk_fma_f32 v[128:129], v[246:247], v[88:89], v[128:129]
	v_pk_fma_f32 v[128:129], v[248:249], v[90:91], v[128:129]
	v_add_f32_e32 v126, v128, v129
	v_pk_mul_f32 v[242:243], v[242:243], v[92:93]
	v_pk_mul_f32 v[244:245], v[244:245], v[94:95]
	v_pk_mul_f32 v[246:247], v[246:247], v[96:97]
	v_pk_mul_f32 v[248:249], v[248:249], v[98:99]
	v_add_f32_dpp v126, v126, v126 quad_perm:[1,0,3,2] row_mask:0xf bank_mask:0xf bound_ctrl:1
	s_nop 0
	s_nop 0
	v_add_f32_dpp v126, v126, v126 quad_perm:[2,3,0,1] row_mask:0xf bank_mask:0xf bound_ctrl:1
	s_nop 0
	s_nop 0
	v_add_f32_dpp v126, v126, v126 row_half_mirror row_mask:0xf bank_mask:0xf bound_ctrl:1
	v_pk_fma_f32 v[242:243], v[100:101], v[126:127], v[242:243] op_sel_hi:[1,0,1]
	v_pk_fma_f32 v[244:245], v[102:103], v[126:127], v[244:245] op_sel_hi:[1,0,1]
	v_pk_fma_f32 v[246:247], v[104:105], v[126:127], v[246:247] op_sel_hi:[1,0,1]
	v_pk_fma_f32 v[248:249], v[106:107], v[126:127], v[248:249] op_sel_hi:[1,0,1]
	v_pk_fma_f32 v[242:243], v[108:109], v[124:125], v[242:243] op_sel_hi:[1,0,1]
	v_pk_fma_f32 v[244:245], v[110:111], v[124:125], v[244:245] op_sel_hi:[1,0,1]
	v_pk_fma_f32 v[246:247], v[112:113], v[124:125], v[246:247] op_sel_hi:[1,0,1]
	v_pk_fma_f32 v[248:249], v[114:115], v[124:125], v[248:249] op_sel_hi:[1,0,1]
	v_pk_mul_f32 v[128:129], v[242:243], v[116:117]
	v_pk_fma_f32 v[128:129], v[244:245], v[118:119], v[128:129]
	v_pk_fma_f32 v[128:129], v[246:247], v[120:121], v[128:129]
	v_pk_fma_f32 v[128:129], v[248:249], v[122:123], v[128:129]
	v_add_f32_e32 v130, v128, v129
	global_store_dwordx4 v[236:237], v[242:245], off
	global_store_dwordx4 v[236:237], v[246:249], off offset:128
	v_add_f32_dpp v130, v130, v130 quad_perm:[1,0,3,2] row_mask:0xf bank_mask:0xf bound_ctrl:1
	s_nop 0
	s_nop 0
	v_add_f32_dpp v130, v130, v130 quad_perm:[2,3,0,1] row_mask:0xf bank_mask:0xf bound_ctrl:1
	s_nop 0
	s_nop 0
	v_add_f32_dpp v130, v130, v130 row_half_mirror row_mask:0xf bank_mask:0xf bound_ctrl:1
	s_mov_b64 s[52:53], 0x2000
	v_lshl_add_u64 v[236:237], v[236:237], 0, s[52:53]
	ds_write_b32 v205, v130

.Lhs_nofin:
	s_cmp_eq_u32 s34, 0
	s_cbranch_scc1 .Lcv_noproc
	s_mov_b32 s62, 0x55555555
	s_mov_b32 s63, 0x55555555
	s_cmp_eq_u32 s35, 0
	s_cbranch_scc1 .Lcv_noscale
	v_mul_f32_e32 v242, v242, v223
	v_mul_f32_e32 v243, v243, v223
	v_mul_f32_e32 v244, v244, v223
	v_mul_f32_e32 v245, v245, v223
	v_mul_f32_e32 v246, v246, v223
	v_mul_f32_e32 v247, v247, v223
	v_mul_f32_e32 v248, v248, v223
	v_mul_f32_e32 v249, v249, v223
	v_mul_f32_e32 v236, v236, v223
	v_mul_f32_e32 v237, v237, v223
	v_mul_f32_e32 v238, v238, v223
	v_mul_f32_e32 v239, v239, v223
	v_mul_f32_e32 v224, v224, v223
	v_mul_f32_e32 v225, v225, v223
	v_mul_f32_e32 v226, v226, v223
	v_mul_f32_e32 v227, v227, v223

.Lcv_noproc:
	s_mov_b32 s34, 0
	s_sub_u32 s54, s12, 18
	s_cmp_lt_u32 s54, 0x40
	s_cbranch_scc0 .Lcv_noitem
	s_lshl_b32 s54, s54, 10
	s_lshl_b32 s53, s8, 2
	s_add_i32 s53, s53, s11
	s_add_i32 s53, s53, -4
	s_add_i32 s54, s54, s53
	s_mov_b32 s55, 0x2500
	s_cmp_eq_u32 s30, 0
	s_cselect_b32 s55, 0x4600, s55
	s_cmp_lt_u32 s54, s55
	s_cbranch_scc0 .Lcv_noitem
	s_lshl_b32 s61, s30, 12
	s_cmp_lt_u32 s54, 0x400
	s_cbranch_scc0 .Lcv_j1
	v_readlane_b32 s58, v255, 17
	v_readlane_b32 s59, v255, 18
	s_lshl_b32 s4, s30, 22
	s_mov_b32 s60, 0x2100000
	s_mov_b32 s57, 0
	s_branch .Lcv_jsel

.Lcv_j4:
	s_sub_u32 s54, s54, 0x3b00
	v_readlane_b32 s58, v254, 51
	v_readlane_b32 s59, v254, 52
	s_mov_b32 s4, 0xb00000
	s_mov_b32 s60, 0xb00000
	s_mov_b32 s57, 2
	s_branch .Lcv_jsel

.Lcv_shdone:
	s_lshl_b32 s14, s56, 6
	s_mul_i32 s4, s14, s1
	s_lshl_b32 s0, s0, 2
	s_add_i32 s4, s4, s0
	s_add_u32 s58, s58, s4
	s_addc_u32 s59, s59, 0
	v_mul_u32_u24_e32 v84, s1, v231
	global_load_dwordx4 v[242:245], v84, s[58:59]
	global_load_dwordx4 v[246:249], v84, s[58:59] offset:16
	global_load_dwordx4 v[236:239], v84, s[58:59] offset:32
	global_load_dwordx4 v[224:227], v84, s[58:59] offset:48
	s_cmp_eq_u32 s35, 0
	s_cbranch_scc1 .Lcv_nosl
	s_lshl_b32 s4, s14, 2
	s_add_u32 s6, s6, s4
	s_addc_u32 s7, s7, 0
	global_load_dword v223, v50, s[6:7]
.Lcv_nosl:
	s_lshl_b32 s4, s55, 4
	s_mul_i32 s4, s4, s5
	s_add_i32 s4, s4, s14
	s_lshl_b32 s4, s4, 1
	s_add_u32 s50, s86, s60
	s_addc_u32 s51, s87, 0
	s_add_u32 s50, s50, s4
	s_addc_u32 s51, s51, 0
	s_lshl_b32 s52, s5, 2
	s_lshl_b32 s4, s5, 1
	v_mul_u32_u24_e32 v232, s4, v51
	v_add_u32_e32 v232, v232, v233
	s_mov_b32 s34, 1
